# accumulator zeroing with v_mov_b64 pairs (64 instead of 128 moves per GEMM unit start), on v14
# speedup vs baseline: 1.0146x; 1.0032x over previous
.LBB0_123:
	s_ashr_i32 s19, s18, 31
	v_readlane_b32 s56, v246, 20
	s_lshl_b64 s[20:21], s[18:19], 19
	v_readlane_b32 s70, v246, 34
	v_readlane_b32 s71, v246, 35
	s_add_u32 s20, s70, s20
	s_addc_u32 s21, s71, s21
	s_and_b64 s[22:23], s[0:1], exec
	s_cselect_b32 s5, s21, s3
	s_cselect_b32 s19, s20, s2
	s_ashr_i32 s17, s16, 31
	s_lshl_b64 s[22:23], s[16:17], 19
	s_add_u32 s22, s15, s22
	s_addc_u32 s23, s30, s23
	s_and_b64 s[28:29], s[0:1], exec
	s_cselect_b32 s17, s23, s27
	s_cselect_b32 s25, s22, s26
	s_add_u32 s2, s2, 0x40080
	s_addc_u32 s3, s3, 0
	s_add_u32 s33, s26, 0x100
	v_mov_b64_e32 v[0:1], 0
	s_addc_u32 s46, s27, 0
	s_mov_b32 s47, -2
	v_mov_b64_e32 v[2:3], 0
	v_mov_b64_e32 v[4:5], 0
	v_mov_b64_e32 v[6:7], 0
	v_mov_b64_e32 v[16:17], 0
	v_mov_b64_e32 v[18:19], 0
	v_mov_b64_e32 v[20:21], 0
	v_mov_b64_e32 v[22:23], 0
	v_mov_b64_e32 v[32:33], 0
	v_mov_b64_e32 v[34:35], 0
	v_mov_b64_e32 v[36:37], 0
	v_mov_b64_e32 v[38:39], 0
	v_mov_b64_e32 v[48:49], 0
	v_mov_b64_e32 v[50:51], 0
	v_mov_b64_e32 v[52:53], 0
	v_mov_b64_e32 v[54:55], 0
	v_mov_b64_e32 v[8:9], 0
	v_mov_b64_e32 v[10:11], 0
	v_mov_b64_e32 v[12:13], 0
	v_mov_b64_e32 v[14:15], 0
	v_mov_b64_e32 v[24:25], 0
	v_mov_b64_e32 v[26:27], 0
	v_mov_b64_e32 v[28:29], 0
	v_mov_b64_e32 v[30:31], 0
	v_mov_b64_e32 v[40:41], 0
	v_mov_b64_e32 v[42:43], 0
	v_mov_b64_e32 v[44:45], 0
	v_mov_b64_e32 v[46:47], 0
	v_mov_b64_e32 v[56:57], 0
	v_mov_b64_e32 v[58:59], 0
	v_mov_b64_e32 v[60:61], 0
	v_mov_b64_e32 v[62:63], 0
	v_mov_b64_e32 v[64:65], 0
	v_mov_b64_e32 v[66:67], 0
	v_mov_b64_e32 v[68:69], 0
	v_mov_b64_e32 v[70:71], 0
	v_mov_b64_e32 v[80:81], 0
	v_mov_b64_e32 v[82:83], 0
	v_mov_b64_e32 v[84:85], 0
	v_mov_b64_e32 v[86:87], 0
	v_mov_b64_e32 v[96:97], 0
	v_mov_b64_e32 v[98:99], 0
	v_mov_b64_e32 v[100:101], 0
	v_mov_b64_e32 v[102:103], 0
	v_mov_b64_e32 v[112:113], 0
	v_mov_b64_e32 v[114:115], 0
	v_mov_b64_e32 v[116:117], 0
	v_mov_b64_e32 v[118:119], 0
	v_mov_b64_e32 v[72:73], 0
	v_mov_b64_e32 v[74:75], 0
	v_mov_b64_e32 v[76:77], 0
	v_mov_b64_e32 v[78:79], 0
	v_mov_b64_e32 v[88:89], 0
	v_mov_b64_e32 v[90:91], 0
	v_mov_b64_e32 v[92:93], 0
	v_mov_b64_e32 v[94:95], 0
	v_mov_b64_e32 v[104:105], 0
	v_mov_b64_e32 v[106:107], 0
	v_mov_b64_e32 v[108:109], 0
	v_mov_b64_e32 v[110:111], 0
	v_mov_b64_e32 v[120:121], 0
	v_mov_b64_e32 v[122:123], 0
	v_mov_b64_e32 v[124:125], 0
	v_mov_b64_e32 v[126:127], 0
	v_readlane_b32 s57, v246, 21
	v_readlane_b32 s58, v246, 22
	v_readlane_b32 s59, v246, 23
	v_readlane_b32 s60, v246, 24
	v_readlane_b32 s61, v246, 25
	v_readlane_b32 s62, v246, 26
	v_readlane_b32 s63, v246, 27
	v_readlane_b32 s64, v246, 28
	v_readlane_b32 s65, v246, 29
	v_readlane_b32 s66, v246, 30
	v_readlane_b32 s67, v246, 31
	v_readlane_b32 s68, v246, 32
	v_readlane_b32 s69, v246, 33

.LBB0_456:
	v_readlane_b32 s56, v246, 20
	v_readlane_b32 s60, v246, 24
	v_readlane_b32 s61, v246, 25
	v_readlane_b32 s62, v246, 26
	v_readlane_b32 s63, v246, 27
	v_readlane_b32 s68, v246, 32
	v_readlane_b32 s69, v246, 33
	s_ashr_i32 s13, s12, 31
	v_readlane_b32 s70, v246, 34
	v_readlane_b32 s71, v246, 35
	s_mov_b64 s[60:61], s[68:69]
	s_lshl_b64 s[14:15], s[12:13], 19
	s_mov_b64 s[62:63], s[70:71]
	s_add_u32 s14, s62, s14
	s_addc_u32 s15, s63, s15
	s_and_b64 s[16:17], s[0:1], exec
	s_cselect_b32 s13, s15, s21
	s_cselect_b32 s42, s14, s20
	s_ashr_i32 s11, s10, 31
	s_lshl_b64 s[16:17], s[10:11], 19
	v_readlane_b32 s24, v246, 36
	v_readlane_b32 s25, v246, 37
	s_add_u32 s16, s24, s16
	s_addc_u32 s17, s25, s17
	s_and_b64 s[24:25], s[0:1], exec
	s_cselect_b32 s11, s17, s23
	s_cselect_b32 s43, s16, s22
	s_add_u32 s20, s20, 0x40080
	s_addc_u32 s21, s21, 0
	s_add_u32 s44, s22, 0x100
	v_mov_b64_e32 v[0:1], 0
	s_addc_u32 s45, s23, 0
	s_mov_b32 s46, -2
	v_mov_b64_e32 v[2:3], 0
	v_mov_b64_e32 v[4:5], 0
	v_mov_b64_e32 v[6:7], 0
	v_mov_b64_e32 v[8:9], 0
	v_mov_b64_e32 v[10:11], 0
	v_mov_b64_e32 v[16:17], 0
	v_mov_b64_e32 v[18:19], 0
	v_mov_b64_e32 v[24:25], 0
	v_mov_b64_e32 v[26:27], 0
	v_mov_b64_e32 v[32:33], 0
	v_mov_b64_e32 v[34:35], 0
	v_mov_b64_e32 v[40:41], 0
	v_mov_b64_e32 v[42:43], 0
	v_mov_b64_e32 v[48:49], 0
	v_mov_b64_e32 v[50:51], 0
	v_mov_b64_e32 v[12:13], 0
	v_mov_b64_e32 v[14:15], 0
	v_mov_b64_e32 v[20:21], 0
	v_mov_b64_e32 v[22:23], 0
	v_mov_b64_e32 v[28:29], 0
	v_mov_b64_e32 v[30:31], 0
	v_mov_b64_e32 v[36:37], 0
	v_mov_b64_e32 v[38:39], 0
	v_mov_b64_e32 v[44:45], 0
	v_mov_b64_e32 v[46:47], 0
	v_mov_b64_e32 v[52:53], 0
	v_mov_b64_e32 v[54:55], 0
	v_mov_b64_e32 v[56:57], 0
	v_mov_b64_e32 v[58:59], 0
	v_mov_b64_e32 v[60:61], 0
	v_mov_b64_e32 v[62:63], 0
	v_mov_b64_e32 v[64:65], 0
	v_mov_b64_e32 v[66:67], 0
	v_mov_b64_e32 v[68:69], 0
	v_mov_b64_e32 v[70:71], 0
	v_mov_b64_e32 v[72:73], 0
	v_mov_b64_e32 v[74:75], 0
	v_mov_b64_e32 v[80:81], 0
	v_mov_b64_e32 v[82:83], 0
	v_mov_b64_e32 v[88:89], 0
	v_mov_b64_e32 v[90:91], 0
	v_mov_b64_e32 v[96:97], 0
	v_mov_b64_e32 v[98:99], 0
	v_mov_b64_e32 v[104:105], 0
	v_mov_b64_e32 v[106:107], 0
	v_mov_b64_e32 v[112:113], 0
	v_mov_b64_e32 v[114:115], 0
	v_mov_b64_e32 v[76:77], 0
	v_mov_b64_e32 v[78:79], 0
	v_mov_b64_e32 v[84:85], 0
	v_mov_b64_e32 v[86:87], 0
	v_mov_b64_e32 v[92:93], 0
	v_mov_b64_e32 v[94:95], 0
	v_mov_b64_e32 v[100:101], 0
	v_mov_b64_e32 v[102:103], 0
	v_mov_b64_e32 v[108:109], 0
	v_mov_b64_e32 v[110:111], 0
	v_mov_b64_e32 v[116:117], 0
	v_mov_b64_e32 v[118:119], 0
	v_mov_b64_e32 v[120:121], 0
	v_mov_b64_e32 v[122:123], 0
	v_mov_b64_e32 v[124:125], 0
	v_mov_b64_e32 v[126:127], 0
	v_readlane_b32 s57, v246, 21
	v_readlane_b32 s58, v246, 22
	v_readlane_b32 s59, v246, 23
	v_readlane_b32 s64, v246, 28
	v_readlane_b32 s65, v246, 29
	v_readlane_b32 s66, v246, 30
	v_readlane_b32 s67, v246, 31

.LBB0_645:
	v_readlane_b32 s52, v246, 20
	v_readlane_b32 s60, v246, 28
	v_readlane_b32 s61, v246, 29
	v_readlane_b32 s62, v246, 30
	v_readlane_b32 s63, v246, 31
	v_readlane_b32 s64, v246, 32
	v_readlane_b32 s65, v246, 33
	s_ashr_i32 s17, s16, 31
	v_readlane_b32 s66, v246, 34
	v_readlane_b32 s67, v246, 35
	s_mov_b64 s[60:61], s[64:65]
	s_andn2_b64 vcc, exec, s[34:35]
	s_lshl_b64 s[20:21], s[16:17], 19
	s_mov_b64 s[62:63], s[66:67]
	s_add_u32 s20, s62, s20
	s_addc_u32 s21, s63, s21
	s_and_b64 s[22:23], s[34:35], exec
	s_cselect_b32 s17, s21, s27
	s_cselect_b32 s50, s20, s26
	s_ashr_i32 s19, s18, 31
	s_lshl_b64 s[22:23], s[18:19], 19
	s_add_u32 s22, s38, s22
	s_addc_u32 s23, s40, s23
	v_cndmask_b32_e64 v0, 0, 1, s[34:35]
	s_and_b64 s[34:35], s[34:35], exec
	s_cselect_b32 s19, s23, s29
	s_cselect_b32 s51, s22, s28
	s_add_u32 s26, s26, 0x40080
	s_addc_u32 s27, s27, 0
	v_cmp_ne_u32_e64 s[0:1], 1, v0
	v_readlane_b32 s53, v246, 21
	v_readlane_b32 s54, v246, 22
	s_add_u32 s52, s28, 0x100
	v_mov_b64_e32 v[0:1], 0
	s_addc_u32 s53, s29, 0
	s_mov_b32 s54, -2
	v_mov_b64_e32 v[2:3], 0
	v_mov_b64_e32 v[4:5], 0
	v_mov_b64_e32 v[6:7], 0
	v_mov_b64_e32 v[16:17], 0
	v_mov_b64_e32 v[18:19], 0
	v_mov_b64_e32 v[20:21], 0
	v_mov_b64_e32 v[22:23], 0
	v_mov_b64_e32 v[32:33], 0
	v_mov_b64_e32 v[34:35], 0
	v_mov_b64_e32 v[36:37], 0
	v_mov_b64_e32 v[38:39], 0
	v_mov_b64_e32 v[48:49], 0
	v_mov_b64_e32 v[50:51], 0
	v_mov_b64_e32 v[52:53], 0
	v_mov_b64_e32 v[54:55], 0
	v_mov_b64_e32 v[8:9], 0
	v_mov_b64_e32 v[10:11], 0
	v_mov_b64_e32 v[12:13], 0
	v_mov_b64_e32 v[14:15], 0
	v_mov_b64_e32 v[24:25], 0
	v_mov_b64_e32 v[26:27], 0
	v_mov_b64_e32 v[28:29], 0
	v_mov_b64_e32 v[30:31], 0
	v_mov_b64_e32 v[40:41], 0
	v_mov_b64_e32 v[42:43], 0
	v_mov_b64_e32 v[44:45], 0
	v_mov_b64_e32 v[46:47], 0
	v_mov_b64_e32 v[56:57], 0
	v_mov_b64_e32 v[58:59], 0
	v_mov_b64_e32 v[60:61], 0
	v_mov_b64_e32 v[62:63], 0
	v_mov_b64_e32 v[64:65], 0
	v_mov_b64_e32 v[66:67], 0
	v_mov_b64_e32 v[68:69], 0
	v_mov_b64_e32 v[70:71], 0
	v_mov_b64_e32 v[80:81], 0
	v_mov_b64_e32 v[82:83], 0
	v_mov_b64_e32 v[84:85], 0
	v_mov_b64_e32 v[86:87], 0
	v_mov_b64_e32 v[96:97], 0
	v_mov_b64_e32 v[98:99], 0
	v_mov_b64_e32 v[100:101], 0
	v_mov_b64_e32 v[102:103], 0
	v_mov_b64_e32 v[112:113], 0
	v_mov_b64_e32 v[114:115], 0
	v_mov_b64_e32 v[116:117], 0
	v_mov_b64_e32 v[118:119], 0
	v_mov_b64_e32 v[72:73], 0
	v_mov_b64_e32 v[74:75], 0
	v_mov_b64_e32 v[76:77], 0
	v_mov_b64_e32 v[78:79], 0
	v_mov_b64_e32 v[88:89], 0
	v_mov_b64_e32 v[90:91], 0
	v_mov_b64_e32 v[92:93], 0
	v_mov_b64_e32 v[94:95], 0
	v_mov_b64_e32 v[104:105], 0
	v_mov_b64_e32 v[106:107], 0
	v_mov_b64_e32 v[108:109], 0
	v_mov_b64_e32 v[110:111], 0
	v_mov_b64_e32 v[120:121], 0
	v_mov_b64_e32 v[122:123], 0
	v_mov_b64_e32 v[124:125], 0
	v_mov_b64_e32 v[126:127], 0
	v_readlane_b32 s55, v246, 23
	v_readlane_b32 s56, v246, 24
	v_readlane_b32 s57, v246, 25
	v_readlane_b32 s58, v246, 26
	v_readlane_b32 s59, v246, 27

.LBB0_665:
	s_ashr_i32 s19, s18, 31
	s_lshl_b64 s[20:21], s[18:19], 18
	s_add_u32 s20, s30, s20
	s_addc_u32 s21, s31, s21
	s_and_b64 s[22:23], s[2:3], exec
	s_cselect_b32 s19, s21, s27
	s_cselect_b32 s50, s20, s26
	s_ashr_i32 s17, s16, 31
	s_lshl_b64 s[22:23], s[16:17], 18
	v_readlane_b32 s34, v246, 38
	v_readlane_b32 s35, v246, 39
	s_add_u32 s22, s34, s22
	s_addc_u32 s23, s35, s23
	s_and_b64 s[34:35], s[2:3], exec
	s_cselect_b32 s17, s23, s29
	s_cselect_b32 s51, s22, s28
	s_add_u32 s26, s26, 0x20080
	s_addc_u32 s27, s27, 0
	s_add_u32 s52, s28, 0x100
	v_mov_b64_e32 v[0:1], 0
	s_addc_u32 s53, s29, 0
	s_mov_b32 s54, -2
	v_mov_b64_e32 v[2:3], 0
	v_mov_b64_e32 v[4:5], 0
	v_mov_b64_e32 v[6:7], 0
	v_mov_b64_e32 v[8:9], 0
	v_mov_b64_e32 v[10:11], 0
	v_mov_b64_e32 v[12:13], 0
	v_mov_b64_e32 v[14:15], 0
	v_mov_b64_e32 v[24:25], 0
	v_mov_b64_e32 v[26:27], 0
	v_mov_b64_e32 v[28:29], 0
	v_mov_b64_e32 v[30:31], 0
	v_mov_b64_e32 v[48:49], 0
	v_mov_b64_e32 v[50:51], 0
	v_mov_b64_e32 v[52:53], 0
	v_mov_b64_e32 v[54:55], 0
	v_mov_b64_e32 v[16:17], 0
	v_mov_b64_e32 v[18:19], 0
	v_mov_b64_e32 v[20:21], 0
	v_mov_b64_e32 v[22:23], 0
	v_mov_b64_e32 v[32:33], 0
	v_mov_b64_e32 v[34:35], 0
	v_mov_b64_e32 v[36:37], 0
	v_mov_b64_e32 v[38:39], 0
	v_mov_b64_e32 v[40:41], 0
	v_mov_b64_e32 v[42:43], 0
	v_mov_b64_e32 v[44:45], 0
	v_mov_b64_e32 v[46:47], 0
	v_mov_b64_e32 v[56:57], 0
	v_mov_b64_e32 v[58:59], 0
	v_mov_b64_e32 v[60:61], 0
	v_mov_b64_e32 v[62:63], 0
	v_mov_b64_e32 v[64:65], 0
	v_mov_b64_e32 v[66:67], 0
	v_mov_b64_e32 v[68:69], 0
	v_mov_b64_e32 v[70:71], 0
	v_mov_b64_e32 v[80:81], 0
	v_mov_b64_e32 v[82:83], 0
	v_mov_b64_e32 v[84:85], 0
	v_mov_b64_e32 v[86:87], 0
	v_mov_b64_e32 v[96:97], 0
	v_mov_b64_e32 v[98:99], 0
	v_mov_b64_e32 v[100:101], 0
	v_mov_b64_e32 v[102:103], 0
	v_mov_b64_e32 v[108:109], 0
	v_mov_b64_e32 v[110:111], 0
	v_mov_b64_e32 v[116:117], 0
	v_mov_b64_e32 v[118:119], 0
	v_mov_b64_e32 v[72:73], 0
	v_mov_b64_e32 v[74:75], 0
	v_mov_b64_e32 v[76:77], 0
	v_mov_b64_e32 v[78:79], 0
	v_mov_b64_e32 v[88:89], 0
	v_mov_b64_e32 v[90:91], 0
	v_mov_b64_e32 v[92:93], 0
	v_mov_b64_e32 v[94:95], 0
	v_mov_b64_e32 v[104:105], 0
	v_mov_b64_e32 v[106:107], 0
	v_mov_b64_e32 v[112:113], 0
	v_mov_b64_e32 v[114:115], 0
	v_mov_b64_e32 v[120:121], 0
	v_mov_b64_e32 v[122:123], 0
	v_mov_b64_e32 v[124:125], 0
	v_mov_b64_e32 v[126:127], 0

.LBB0_685:
	s_ashr_i32 s23, s22, 31
	s_lshl_b64 s[24:25], s[22:23], 19
	s_add_u32 s24, s72, s24
	s_addc_u32 s25, s73, s25
	s_and_b64 s[26:27], s[0:1], exec
	s_cselect_b32 s23, s25, s31
	s_cselect_b32 s49, s24, s30
	s_ashr_i32 s21, s20, 31
	s_lshl_b64 s[26:27], s[20:21], 19
	v_readlane_b32 s36, v246, 40
	v_readlane_b32 s37, v246, 41
	s_add_u32 s26, s36, s26
	s_addc_u32 s27, s37, s27
	s_and_b64 s[36:37], s[0:1], exec
	s_cselect_b32 s21, s27, s35
	s_cselect_b32 s50, s26, s34
	s_add_u32 s30, s30, 0x40080
	s_addc_u32 s31, s31, 0
	s_add_u32 s51, s34, 0x100
	v_mov_b64_e32 v[0:1], 0
	s_addc_u32 s52, s35, 0
	s_mov_b32 s53, -2
	v_mov_b64_e32 v[2:3], 0
	v_mov_b64_e32 v[4:5], 0
	v_mov_b64_e32 v[6:7], 0
	v_mov_b64_e32 v[16:17], 0
	v_mov_b64_e32 v[18:19], 0
	v_mov_b64_e32 v[20:21], 0
	v_mov_b64_e32 v[22:23], 0
	v_mov_b64_e32 v[32:33], 0
	v_mov_b64_e32 v[34:35], 0
	v_mov_b64_e32 v[36:37], 0
	v_mov_b64_e32 v[38:39], 0
	v_mov_b64_e32 v[48:49], 0
	v_mov_b64_e32 v[50:51], 0
	v_mov_b64_e32 v[52:53], 0
	v_mov_b64_e32 v[54:55], 0
	v_mov_b64_e32 v[8:9], 0
	v_mov_b64_e32 v[10:11], 0
	v_mov_b64_e32 v[12:13], 0
	v_mov_b64_e32 v[14:15], 0
	v_mov_b64_e32 v[24:25], 0
	v_mov_b64_e32 v[26:27], 0
	v_mov_b64_e32 v[28:29], 0
	v_mov_b64_e32 v[30:31], 0
	v_mov_b64_e32 v[40:41], 0
	v_mov_b64_e32 v[42:43], 0
	v_mov_b64_e32 v[44:45], 0
	v_mov_b64_e32 v[46:47], 0
	v_mov_b64_e32 v[56:57], 0
	v_mov_b64_e32 v[58:59], 0
	v_mov_b64_e32 v[60:61], 0
	v_mov_b64_e32 v[62:63], 0
	v_mov_b64_e32 v[64:65], 0
	v_mov_b64_e32 v[66:67], 0
	v_mov_b64_e32 v[68:69], 0
	v_mov_b64_e32 v[70:71], 0
	v_mov_b64_e32 v[80:81], 0
	v_mov_b64_e32 v[82:83], 0
	v_mov_b64_e32 v[84:85], 0
	v_mov_b64_e32 v[86:87], 0
	v_mov_b64_e32 v[96:97], 0
	v_mov_b64_e32 v[98:99], 0
	v_mov_b64_e32 v[100:101], 0
	v_mov_b64_e32 v[102:103], 0
	v_mov_b64_e32 v[112:113], 0
	v_mov_b64_e32 v[114:115], 0
	v_mov_b64_e32 v[116:117], 0
	v_mov_b64_e32 v[118:119], 0
	v_mov_b64_e32 v[72:73], 0
	v_mov_b64_e32 v[74:75], 0
	v_mov_b64_e32 v[76:77], 0
	v_mov_b64_e32 v[78:79], 0
	v_mov_b64_e32 v[88:89], 0
	v_mov_b64_e32 v[90:91], 0
	v_mov_b64_e32 v[92:93], 0
	v_mov_b64_e32 v[94:95], 0
	v_mov_b64_e32 v[104:105], 0
	v_mov_b64_e32 v[106:107], 0
	v_mov_b64_e32 v[108:109], 0
	v_mov_b64_e32 v[110:111], 0
	v_mov_b64_e32 v[120:121], 0
	v_mov_b64_e32 v[122:123], 0
	v_mov_b64_e32 v[124:125], 0
	v_mov_b64_e32 v[126:127], 0

.LBB0_757:
	s_ashr_i32 s25, s24, 31
	s_lshl_b64 s[26:27], s[24:25], 19
	s_add_u32 s26, s94, s26
	s_addc_u32 s27, s95, s27
	s_and_b64 s[28:29], s[2:3], exec
	s_cselect_b32 s25, s27, s35
	s_cselect_b32 s54, s26, s34
	s_ashr_i32 s23, s22, 31
	s_lshl_b64 s[28:29], s[22:23], 19
	v_readlane_b32 s38, v246, 42
	v_readlane_b32 s39, v246, 43
	s_add_u32 s28, s38, s28
	s_addc_u32 s29, s39, s29
	s_and_b64 s[38:39], s[2:3], exec
	s_cselect_b32 s23, s29, s37
	s_cselect_b32 s55, s28, s36
	s_add_u32 s34, s34, 0x40080
	s_addc_u32 s35, s35, 0
	s_add_u32 s56, s36, 0x100
	v_mov_b64_e32 v[0:1], 0
	s_addc_u32 s57, s37, 0
	s_mov_b32 s60, -2
	v_mov_b64_e32 v[2:3], 0
	v_mov_b64_e32 v[4:5], 0
	v_mov_b64_e32 v[6:7], 0
	v_mov_b64_e32 v[16:17], 0
	v_mov_b64_e32 v[18:19], 0
	v_mov_b64_e32 v[20:21], 0
	v_mov_b64_e32 v[22:23], 0
	v_mov_b64_e32 v[32:33], 0
	v_mov_b64_e32 v[34:35], 0
	v_mov_b64_e32 v[36:37], 0
	v_mov_b64_e32 v[38:39], 0
	v_mov_b64_e32 v[48:49], 0
	v_mov_b64_e32 v[50:51], 0
	v_mov_b64_e32 v[52:53], 0
	v_mov_b64_e32 v[54:55], 0
	v_mov_b64_e32 v[8:9], 0
	v_mov_b64_e32 v[10:11], 0
	v_mov_b64_e32 v[12:13], 0
	v_mov_b64_e32 v[14:15], 0
	v_mov_b64_e32 v[24:25], 0
	v_mov_b64_e32 v[26:27], 0
	v_mov_b64_e32 v[28:29], 0
	v_mov_b64_e32 v[30:31], 0
	v_mov_b64_e32 v[40:41], 0
	v_mov_b64_e32 v[42:43], 0
	v_mov_b64_e32 v[44:45], 0
	v_mov_b64_e32 v[46:47], 0
	v_mov_b64_e32 v[56:57], 0
	v_mov_b64_e32 v[58:59], 0
	v_mov_b64_e32 v[60:61], 0
	v_mov_b64_e32 v[62:63], 0
	v_mov_b64_e32 v[64:65], 0
	v_mov_b64_e32 v[66:67], 0
	v_mov_b64_e32 v[68:69], 0
	v_mov_b64_e32 v[70:71], 0
	v_mov_b64_e32 v[80:81], 0
	v_mov_b64_e32 v[82:83], 0
	v_mov_b64_e32 v[84:85], 0
	v_mov_b64_e32 v[86:87], 0
	v_mov_b64_e32 v[96:97], 0
	v_mov_b64_e32 v[98:99], 0
	v_mov_b64_e32 v[100:101], 0
	v_mov_b64_e32 v[102:103], 0
	v_mov_b64_e32 v[112:113], 0
	v_mov_b64_e32 v[114:115], 0
	v_mov_b64_e32 v[116:117], 0
	v_mov_b64_e32 v[118:119], 0
	v_mov_b64_e32 v[72:73], 0
	v_mov_b64_e32 v[74:75], 0
	v_mov_b64_e32 v[76:77], 0
	v_mov_b64_e32 v[78:79], 0
	v_mov_b64_e32 v[88:89], 0
	v_mov_b64_e32 v[90:91], 0
	v_mov_b64_e32 v[92:93], 0
	v_mov_b64_e32 v[94:95], 0
	v_mov_b64_e32 v[104:105], 0
	v_mov_b64_e32 v[106:107], 0
	v_mov_b64_e32 v[108:109], 0
	v_mov_b64_e32 v[110:111], 0
	v_mov_b64_e32 v[120:121], 0
	v_mov_b64_e32 v[122:123], 0
	v_mov_b64_e32 v[124:125], 0
	v_mov_b64_e32 v[126:127], 0

.LBB0_778:
	v_add_u32_e32 v147, s43, v145
	ds_read_b128 v[148:151], v147
	ds_read_b128 v[152:155], v147 offset:1024
	ds_read_b128 v[156:159], v147 offset:2048
	ds_read_b128 v[160:163], v147 offset:3072
	v_add_u32_e32 v147, s44, v145
	s_add_u32 s26, s12, s24
	ds_read_b128 v[164:167], v147
	ds_read_b128 v[180:183], v147 offset:1024
	ds_read_b128 v[184:187], v147 offset:2048
	ds_read_b128 v[188:191], v147 offset:3072
	s_addc_u32 s27, s13, s25
	s_add_u32 s26, s26, 0x100
	s_addc_u32 s27, s27, 0
	s_add_u32 s51, s46, s24
	s_addc_u32 s52, s47, s25
	s_cmpk_eq_i32 s24, 0x700
	s_cselect_b32 s29, s19, s27
	s_cselect_b32 s28, s48, s26
	s_cselect_b32 s27, s17, s52
	s_cselect_b32 s26, s49, s51
	v_lshl_add_u64 v[168:169], v[140:141], 0, s[24:25]
	s_add_i32 m0, s11, 0xc000
	ds_read_b128 v[192:195], v146
	ds_read_b128 v[196:199], v146 offset:1024
	ds_read_b128 v[200:203], v146 offset:2048
	ds_read_b128 v[204:207], v146 offset:3072
	ds_read_b128 v[208:211], v146 offset:4096
	ds_read_b128 v[212:215], v146 offset:5120
	ds_read_b128 v[216:219], v146 offset:6144
	ds_read_b128 v[220:223], v146 offset:7168
	global_load_lds_dwordx4 v[168:169], off
	v_lshl_add_u64 v[168:169], v[142:143], 0, s[24:25]
	s_add_i32 m0, s11, 0xe000
	s_nop 0
	global_load_lds_dwordx4 v[168:169], off
	s_waitcnt vmcnt(8)
	s_waitcnt lgkmcnt(0)
	s_barrier
	s_waitcnt lgkmcnt(0)
	v_mfma_f32_16x16x32_bf16 v[100:103], v[148:151], v[192:195], v[100:103]
	v_mfma_f32_16x16x32_bf16 v[96:99], v[156:159], v[192:195], v[96:99]
	v_mfma_f32_16x16x32_bf16 v[108:111], v[148:151], v[200:203], v[108:111]
	v_mfma_f32_16x16x32_bf16 v[84:87], v[156:159], v[200:203], v[84:87]
	v_mfma_f32_16x16x32_bf16 v[116:119], v[148:151], v[208:211], v[116:119]
	v_mfma_f32_16x16x32_bf16 v[112:115], v[156:159], v[208:211], v[112:115]
	v_mfma_f32_16x16x32_bf16 v[124:127], v[148:151], v[216:219], v[124:127]
	v_mfma_f32_16x16x32_bf16 v[120:123], v[156:159], v[216:219], v[120:123]
	v_mfma_f32_16x16x32_bf16 v[100:103], v[152:155], v[196:199], v[100:103]
	v_mfma_f32_16x16x32_bf16 v[96:99], v[160:163], v[196:199], v[96:99]
	v_mfma_f32_16x16x32_bf16 v[108:111], v[152:155], v[204:207], v[108:111]
	v_mfma_f32_16x16x32_bf16 v[84:87], v[160:163], v[204:207], v[84:87]
	v_mfma_f32_16x16x32_bf16 v[116:119], v[152:155], v[212:215], v[116:119]
	v_mfma_f32_16x16x32_bf16 v[112:115], v[160:163], v[212:215], v[112:115]
	v_mfma_f32_16x16x32_bf16 v[124:127], v[152:155], v[220:223], v[124:127]
	v_mfma_f32_16x16x32_bf16 v[120:123], v[160:163], v[220:223], v[120:123]
	v_mfma_f32_16x16x32_bf16 v[76:79], v[164:167], v[192:195], v[76:79]
	v_mfma_f32_16x16x32_bf16 v[68:71], v[184:187], v[192:195], v[68:71]
	v_mfma_f32_16x16x32_bf16 v[72:75], v[164:167], v[200:203], v[72:75]
	v_mfma_f32_16x16x32_bf16 v[64:67], v[184:187], v[200:203], v[64:67]
	v_mfma_f32_16x16x32_bf16 v[88:91], v[164:167], v[208:211], v[88:91]
	v_mfma_f32_16x16x32_bf16 v[80:83], v[184:187], v[208:211], v[80:83]
	v_mfma_f32_16x16x32_bf16 v[104:107], v[164:167], v[216:219], v[104:107]
	v_mfma_f32_16x16x32_bf16 v[92:95], v[184:187], v[216:219], v[92:95]
	v_mfma_f32_16x16x32_bf16 v[76:79], v[180:183], v[196:199], v[76:79]
	v_mfma_f32_16x16x32_bf16 v[68:71], v[188:191], v[196:199], v[68:71]
	v_mfma_f32_16x16x32_bf16 v[72:75], v[180:183], v[204:207], v[72:75]
	v_mfma_f32_16x16x32_bf16 v[64:67], v[188:191], v[204:207], v[64:67]
	v_mfma_f32_16x16x32_bf16 v[88:91], v[180:183], v[212:215], v[88:91]
	v_mfma_f32_16x16x32_bf16 v[80:83], v[188:191], v[212:215], v[80:83]
	v_mfma_f32_16x16x32_bf16 v[104:107], v[180:183], v[220:223], v[104:107]
	v_mfma_f32_16x16x32_bf16 v[92:95], v[188:191], v[220:223], v[92:95]
	s_barrier
	s_add_i32 s51, s43, s35
	v_lshl_add_u64 v[168:169], s[26:27], 0, v[128:129]
	s_mov_b32 m0, s51
	ds_read_b128 v[192:195], v146 offset:16384
	ds_read_b128 v[196:199], v146 offset:17408
	ds_read_b128 v[200:203], v146 offset:18432
	ds_read_b128 v[204:207], v146 offset:19456
	ds_read_b128 v[208:211], v146 offset:20480
	ds_read_b128 v[212:215], v146 offset:21504
	ds_read_b128 v[216:219], v146 offset:22528
	ds_read_b128 v[220:223], v146 offset:23552
	global_load_lds_dwordx4 v[168:169], off
	s_add_i32 m0, s51, 0x2000
	s_add_u32 s52, s26, 0x40000
	v_lshl_add_u64 v[224:225], s[26:27], 0, v[130:131]
	s_addc_u32 s53, s27, 0
	s_add_i32 s51, s44, s35
	global_load_lds_dwordx4 v[224:225], off
	v_lshl_add_u64 v[226:227], s[52:53], 0, v[128:129]
	s_mov_b32 m0, s51
	v_lshl_add_u64 v[228:229], s[28:29], 0, v[130:131]
	global_load_lds_dwordx4 v[226:227], off
	v_lshl_add_u64 v[226:227], s[52:53], 0, v[130:131]
	s_add_i32 m0, s51, 0x2000
	s_nop 0
	global_load_lds_dwordx4 v[226:227], off
	v_lshl_add_u64 v[226:227], s[28:29], 0, v[128:129]
	s_mov_b32 m0, s11
	s_nop 0
	global_load_lds_dwordx4 v[226:227], off
	s_mov_b32 m0, s36
	s_nop 0
	global_load_lds_dwordx4 v[228:229], off
	s_waitcnt vmcnt(8)
	s_waitcnt lgkmcnt(0)
	s_barrier
	s_waitcnt lgkmcnt(0)
	v_mfma_f32_16x16x32_bf16 v[60:63], v[148:151], v[192:195], v[60:63]
	v_mfma_f32_16x16x32_bf16 v[56:59], v[156:159], v[192:195], v[56:59]
	v_mfma_f32_16x16x32_bf16 v[44:47], v[148:151], v[200:203], v[44:47]
	v_mfma_f32_16x16x32_bf16 v[40:43], v[156:159], v[200:203], v[40:43]
	v_mfma_f32_16x16x32_bf16 v[28:31], v[148:151], v[208:211], v[28:31]
	v_mfma_f32_16x16x32_bf16 v[24:27], v[156:159], v[208:211], v[24:27]
	v_mfma_f32_16x16x32_bf16 v[12:15], v[148:151], v[216:219], v[12:15]
	v_mfma_f32_16x16x32_bf16 v[8:11], v[156:159], v[216:219], v[8:11]
	v_mfma_f32_16x16x32_bf16 v[60:63], v[152:155], v[196:199], v[60:63]
	v_mfma_f32_16x16x32_bf16 v[56:59], v[160:163], v[196:199], v[56:59]
	v_mfma_f32_16x16x32_bf16 v[44:47], v[152:155], v[204:207], v[44:47]
	v_mfma_f32_16x16x32_bf16 v[40:43], v[160:163], v[204:207], v[40:43]
	v_mfma_f32_16x16x32_bf16 v[28:31], v[152:155], v[212:215], v[28:31]
	v_mfma_f32_16x16x32_bf16 v[24:27], v[160:163], v[212:215], v[24:27]
	v_mfma_f32_16x16x32_bf16 v[12:15], v[152:155], v[220:223], v[12:15]
	v_mfma_f32_16x16x32_bf16 v[8:11], v[160:163], v[220:223], v[8:11]
	v_mfma_f32_16x16x32_bf16 v[52:55], v[164:167], v[192:195], v[52:55]
	v_mfma_f32_16x16x32_bf16 v[48:51], v[184:187], v[192:195], v[48:51]
	v_mfma_f32_16x16x32_bf16 v[36:39], v[164:167], v[200:203], v[36:39]
	v_mfma_f32_16x16x32_bf16 v[32:35], v[184:187], v[200:203], v[32:35]
	v_mfma_f32_16x16x32_bf16 v[20:23], v[164:167], v[208:211], v[20:23]
	v_mfma_f32_16x16x32_bf16 v[16:19], v[184:187], v[208:211], v[16:19]
	v_mfma_f32_16x16x32_bf16 v[4:7], v[164:167], v[216:219], v[4:7]
	v_mfma_f32_16x16x32_bf16 v[0:3], v[184:187], v[216:219], v[0:3]
	v_mfma_f32_16x16x32_bf16 v[52:55], v[180:183], v[196:199], v[52:55]
	v_mfma_f32_16x16x32_bf16 v[48:51], v[188:191], v[196:199], v[48:51]
	v_mfma_f32_16x16x32_bf16 v[36:39], v[180:183], v[204:207], v[36:39]
	v_mfma_f32_16x16x32_bf16 v[32:35], v[188:191], v[204:207], v[32:35]
	v_mfma_f32_16x16x32_bf16 v[20:23], v[180:183], v[212:215], v[20:23]
	v_mfma_f32_16x16x32_bf16 v[16:19], v[188:191], v[212:215], v[16:19]
	v_mfma_f32_16x16x32_bf16 v[4:7], v[180:183], v[220:223], v[4:7]
	v_mfma_f32_16x16x32_bf16 v[0:3], v[188:191], v[220:223], v[0:3]
	s_barrier
	s_add_i32 s51, 0, 0x18000
	v_add_u32_e32 v147, s51, v145
	s_add_i32 s52, 0, 0x1c000
	ds_read_b128 v[148:151], v147
	ds_read_b128 v[152:155], v147 offset:1024
	ds_read_b128 v[156:159], v147 offset:2048
	ds_read_b128 v[160:163], v147 offset:3072
	v_add_u32_e32 v147, s52, v145
	ds_read_b128 v[164:167], v147
	ds_read_b128 v[180:183], v147 offset:1024
	ds_read_b128 v[184:187], v147 offset:2048
	ds_read_b128 v[188:191], v147 offset:3072
	s_add_u32 s28, s28, 0x40000
	s_addc_u32 s29, s29, 0
	s_mov_b32 m0, s37
	v_lshl_add_u64 v[230:231], s[28:29], 0, v[128:129]
	ds_read_b128 v[192:195], v146 offset:32768
	ds_read_b128 v[196:199], v146 offset:33792
	ds_read_b128 v[200:203], v146 offset:34816
	ds_read_b128 v[204:207], v146 offset:35840
	ds_read_b128 v[208:211], v146 offset:36864
	ds_read_b128 v[212:215], v146 offset:37888
	ds_read_b128 v[216:219], v146 offset:38912
	ds_read_b128 v[220:223], v146 offset:39936
	global_load_lds_dwordx4 v[230:231], off
	v_lshl_add_u64 v[230:231], s[28:29], 0, v[130:131]
	s_mov_b32 m0, s38
	s_nop 0
	global_load_lds_dwordx4 v[230:231], off
	s_waitcnt vmcnt(8)
	s_waitcnt lgkmcnt(0)
	s_barrier
	s_waitcnt lgkmcnt(0)
	v_mfma_f32_16x16x32_bf16 v[100:103], v[148:151], v[192:195], v[100:103]
	v_mfma_f32_16x16x32_bf16 v[96:99], v[156:159], v[192:195], v[96:99]
	v_mfma_f32_16x16x32_bf16 v[108:111], v[148:151], v[200:203], v[108:111]
	v_mfma_f32_16x16x32_bf16 v[84:87], v[156:159], v[200:203], v[84:87]
	v_mfma_f32_16x16x32_bf16 v[116:119], v[148:151], v[208:211], v[116:119]
	v_mfma_f32_16x16x32_bf16 v[112:115], v[156:159], v[208:211], v[112:115]
	v_mfma_f32_16x16x32_bf16 v[124:127], v[148:151], v[216:219], v[124:127]
	v_mfma_f32_16x16x32_bf16 v[120:123], v[156:159], v[216:219], v[120:123]
	v_mfma_f32_16x16x32_bf16 v[100:103], v[152:155], v[196:199], v[100:103]
	v_mfma_f32_16x16x32_bf16 v[96:99], v[160:163], v[196:199], v[96:99]
	v_mfma_f32_16x16x32_bf16 v[108:111], v[152:155], v[204:207], v[108:111]
	v_mfma_f32_16x16x32_bf16 v[84:87], v[160:163], v[204:207], v[84:87]
	v_mfma_f32_16x16x32_bf16 v[116:119], v[152:155], v[212:215], v[116:119]
	v_mfma_f32_16x16x32_bf16 v[112:115], v[160:163], v[212:215], v[112:115]
	v_mfma_f32_16x16x32_bf16 v[124:127], v[152:155], v[220:223], v[124:127]
	v_mfma_f32_16x16x32_bf16 v[120:123], v[160:163], v[220:223], v[120:123]
	v_mfma_f32_16x16x32_bf16 v[76:79], v[164:167], v[192:195], v[76:79]
	v_mfma_f32_16x16x32_bf16 v[68:71], v[184:187], v[192:195], v[68:71]
	v_mfma_f32_16x16x32_bf16 v[72:75], v[164:167], v[200:203], v[72:75]
	v_mfma_f32_16x16x32_bf16 v[64:67], v[184:187], v[200:203], v[64:67]
	v_mfma_f32_16x16x32_bf16 v[88:91], v[164:167], v[208:211], v[88:91]
	v_mfma_f32_16x16x32_bf16 v[80:83], v[184:187], v[208:211], v[80:83]
	v_mfma_f32_16x16x32_bf16 v[104:107], v[164:167], v[216:219], v[104:107]
	v_mfma_f32_16x16x32_bf16 v[92:95], v[184:187], v[216:219], v[92:95]
	v_mfma_f32_16x16x32_bf16 v[76:79], v[180:183], v[196:199], v[76:79]
	v_mfma_f32_16x16x32_bf16 v[68:71], v[188:191], v[196:199], v[68:71]
	v_mfma_f32_16x16x32_bf16 v[72:75], v[180:183], v[204:207], v[72:75]
	v_mfma_f32_16x16x32_bf16 v[64:67], v[188:191], v[204:207], v[64:67]
	v_mfma_f32_16x16x32_bf16 v[88:91], v[180:183], v[212:215], v[88:91]
	v_mfma_f32_16x16x32_bf16 v[80:83], v[188:191], v[212:215], v[80:83]
	v_mfma_f32_16x16x32_bf16 v[104:107], v[180:183], v[220:223], v[104:107]
	v_mfma_f32_16x16x32_bf16 v[92:95], v[188:191], v[220:223], v[92:95]
	s_barrier
	s_add_i32 s28, s51, s35
	v_lshl_add_u64 v[168:169], v[168:169], 0, s[14:15]
	s_mov_b32 m0, s28
	ds_read_b128 v[192:195], v146 offset:49152
	ds_read_b128 v[196:199], v146 offset:50176
	ds_read_b128 v[200:203], v146 offset:51200
	ds_read_b128 v[204:207], v146 offset:52224
	ds_read_b128 v[208:211], v146 offset:53248
	ds_read_b128 v[212:215], v146 offset:54272
	ds_read_b128 v[216:219], v146 offset:55296
	ds_read_b128 v[220:223], v146 offset:56320
	global_load_lds_dwordx4 v[168:169], off
	s_add_i32 m0, s28, 0x2000
	s_add_u32 s26, s26, 0x40080
	v_lshl_add_u64 v[168:169], v[224:225], 0, s[14:15]
	s_addc_u32 s27, s27, 0
	s_add_i32 s28, s52, s35
	global_load_lds_dwordx4 v[168:169], off
	v_lshl_add_u64 v[168:169], s[26:27], 0, v[128:129]
	s_mov_b32 m0, s28
	s_nop 0
	global_load_lds_dwordx4 v[168:169], off
	v_lshl_add_u64 v[168:169], s[26:27], 0, v[130:131]
	s_add_i32 m0, s28, 0x2000
	s_nop 0
	global_load_lds_dwordx4 v[168:169], off
	v_lshl_add_u64 v[168:169], v[226:227], 0, s[14:15]
	s_mov_b32 m0, s41
	s_nop 0
	global_load_lds_dwordx4 v[168:169], off
	v_lshl_add_u64 v[168:169], v[228:229], 0, s[14:15]
	s_mov_b32 m0, s42
	s_nop 0
	global_load_lds_dwordx4 v[168:169], off
	s_waitcnt vmcnt(8)
	s_waitcnt lgkmcnt(0)
	s_barrier
	s_waitcnt lgkmcnt(0)
	v_mfma_f32_16x16x32_bf16 v[60:63], v[148:151], v[192:195], v[60:63]
	v_mfma_f32_16x16x32_bf16 v[56:59], v[156:159], v[192:195], v[56:59]
	v_mfma_f32_16x16x32_bf16 v[44:47], v[148:151], v[200:203], v[44:47]
	v_mfma_f32_16x16x32_bf16 v[40:43], v[156:159], v[200:203], v[40:43]
	v_mfma_f32_16x16x32_bf16 v[28:31], v[148:151], v[208:211], v[28:31]
	v_mfma_f32_16x16x32_bf16 v[24:27], v[156:159], v[208:211], v[24:27]
	v_mfma_f32_16x16x32_bf16 v[12:15], v[148:151], v[216:219], v[12:15]
	v_mfma_f32_16x16x32_bf16 v[8:11], v[156:159], v[216:219], v[8:11]
	v_mfma_f32_16x16x32_bf16 v[60:63], v[152:155], v[196:199], v[60:63]
	v_mfma_f32_16x16x32_bf16 v[56:59], v[160:163], v[196:199], v[56:59]
	v_mfma_f32_16x16x32_bf16 v[44:47], v[152:155], v[204:207], v[44:47]
	v_mfma_f32_16x16x32_bf16 v[40:43], v[160:163], v[204:207], v[40:43]
	v_mfma_f32_16x16x32_bf16 v[28:31], v[152:155], v[212:215], v[28:31]
	v_mfma_f32_16x16x32_bf16 v[24:27], v[160:163], v[212:215], v[24:27]
	v_mfma_f32_16x16x32_bf16 v[12:15], v[152:155], v[220:223], v[12:15]
	v_mfma_f32_16x16x32_bf16 v[8:11], v[160:163], v[220:223], v[8:11]
	v_mfma_f32_16x16x32_bf16 v[52:55], v[164:167], v[192:195], v[52:55]
	v_mfma_f32_16x16x32_bf16 v[48:51], v[184:187], v[192:195], v[48:51]
	v_mfma_f32_16x16x32_bf16 v[36:39], v[164:167], v[200:203], v[36:39]
	v_mfma_f32_16x16x32_bf16 v[32:35], v[184:187], v[200:203], v[32:35]
	v_mfma_f32_16x16x32_bf16 v[20:23], v[164:167], v[208:211], v[20:23]
	v_mfma_f32_16x16x32_bf16 v[16:19], v[184:187], v[208:211], v[16:19]
	v_mfma_f32_16x16x32_bf16 v[4:7], v[164:167], v[216:219], v[4:7]
	v_mfma_f32_16x16x32_bf16 v[0:3], v[184:187], v[216:219], v[0:3]
	v_mfma_f32_16x16x32_bf16 v[52:55], v[180:183], v[196:199], v[52:55]
	v_mfma_f32_16x16x32_bf16 v[48:51], v[188:191], v[196:199], v[48:51]
	v_mfma_f32_16x16x32_bf16 v[36:39], v[180:183], v[204:207], v[36:39]
	v_mfma_f32_16x16x32_bf16 v[32:35], v[188:191], v[204:207], v[32:35]
	v_mfma_f32_16x16x32_bf16 v[20:23], v[180:183], v[212:215], v[20:23]
	v_mfma_f32_16x16x32_bf16 v[16:19], v[188:191], v[212:215], v[16:19]
	v_mfma_f32_16x16x32_bf16 v[4:7], v[180:183], v[220:223], v[4:7]
	v_mfma_f32_16x16x32_bf16 v[0:3], v[188:191], v[220:223], v[0:3]
	s_barrier
	s_add_i32 s50, s50, 2
	s_add_u32 s24, s24, 0x100
	s_addc_u32 s25, s25, 0
	s_cmp_gt_u32 s50, 13
	s_cbranch_scc0 .LBB0_778
	s_add_u32 s24, s46, 0xffffff00
	s_addc_u32 s25, s47, -1
	s_andn2_b64 vcc, exec, s[2:3]
	s_cbranch_vccnz .LBB0_781
	v_mov_b64_e32 v[0:1], 0
	s_mov_b32 s4, s16
	s_mov_b32 s10, s18
	s_mov_b64 s[12:13], s[22:23]
	s_mov_b32 s40, s45
	v_mov_b64_e32 v[2:3], 0
	v_mov_b64_e32 v[4:5], 0
	v_mov_b64_e32 v[6:7], 0
	v_mov_b64_e32 v[16:17], 0
	v_mov_b64_e32 v[18:19], 0
	v_mov_b64_e32 v[20:21], 0
	v_mov_b64_e32 v[22:23], 0
	v_mov_b64_e32 v[32:33], 0
	v_mov_b64_e32 v[34:35], 0
	v_mov_b64_e32 v[36:37], 0
	v_mov_b64_e32 v[38:39], 0
	v_mov_b64_e32 v[48:49], 0
	v_mov_b64_e32 v[50:51], 0
	v_mov_b64_e32 v[52:53], 0
	v_mov_b64_e32 v[54:55], 0
	v_mov_b64_e32 v[8:9], 0
	v_mov_b64_e32 v[10:11], 0
	v_mov_b64_e32 v[12:13], 0
	v_mov_b64_e32 v[14:15], 0
	v_mov_b64_e32 v[24:25], 0
	v_mov_b64_e32 v[26:27], 0
	v_mov_b64_e32 v[28:29], 0
	v_mov_b64_e32 v[30:31], 0
	v_mov_b64_e32 v[40:41], 0
	v_mov_b64_e32 v[42:43], 0
	v_mov_b64_e32 v[44:45], 0
	v_mov_b64_e32 v[46:47], 0
	v_mov_b64_e32 v[56:57], 0
	v_mov_b64_e32 v[58:59], 0
	v_mov_b64_e32 v[60:61], 0
	v_mov_b64_e32 v[62:63], 0
	v_mov_b64_e32 v[92:93], 0
	v_mov_b64_e32 v[94:95], 0
	v_mov_b64_e32 v[104:105], 0
	v_mov_b64_e32 v[106:107], 0
	v_mov_b64_e32 v[80:81], 0
	v_mov_b64_e32 v[82:83], 0
	v_mov_b64_e32 v[88:89], 0
	v_mov_b64_e32 v[90:91], 0
	v_mov_b64_e32 v[64:65], 0
	v_mov_b64_e32 v[66:67], 0
	v_mov_b64_e32 v[72:73], 0
	v_mov_b64_e32 v[74:75], 0
	v_mov_b64_e32 v[68:69], 0
	v_mov_b64_e32 v[70:71], 0
	v_mov_b64_e32 v[76:77], 0
	v_mov_b64_e32 v[78:79], 0
	v_mov_b64_e32 v[120:121], 0
	v_mov_b64_e32 v[122:123], 0
	v_mov_b64_e32 v[124:125], 0
	v_mov_b64_e32 v[126:127], 0
	v_mov_b64_e32 v[112:113], 0
	v_mov_b64_e32 v[114:115], 0
	v_mov_b64_e32 v[116:117], 0
	v_mov_b64_e32 v[118:119], 0
	v_mov_b64_e32 v[84:85], 0
	v_mov_b64_e32 v[86:87], 0
	v_mov_b64_e32 v[108:109], 0
	v_mov_b64_e32 v[110:111], 0
	v_mov_b64_e32 v[96:97], 0
	v_mov_b64_e32 v[98:99], 0
	v_mov_b64_e32 v[100:101], 0
	v_mov_b64_e32 v[102:103], 0
	s_branch .LBB0_782

.LBB0_941:
	v_readlane_b32 s44, v246, 20
	v_readlane_b32 s48, v246, 24
	v_readlane_b32 s49, v246, 25
	v_readlane_b32 s50, v246, 26
	v_readlane_b32 s51, v246, 27
	v_readlane_b32 s56, v246, 32
	v_readlane_b32 s57, v246, 33
	s_ashr_i32 s15, s14, 31
	v_readlane_b32 s58, v246, 34
	v_readlane_b32 s59, v246, 35
	s_mov_b64 s[48:49], s[56:57]
	s_lshl_b64 s[16:17], s[14:15], 19
	s_mov_b64 s[50:51], s[58:59]
	s_add_u32 s16, s50, s16
	s_addc_u32 s17, s51, s17
	s_and_b64 s[18:19], s[0:1], exec
	s_cselect_b32 s15, s17, s23
	s_cselect_b32 s44, s16, s22
	s_ashr_i32 s13, s12, 31
	s_lshl_b64 s[18:19], s[12:13], 19
	v_readlane_b32 s26, v246, 44
	v_readlane_b32 s27, v246, 45
	s_add_u32 s18, s26, s18
	s_addc_u32 s19, s27, s19
	v_readlane_b32 s45, v246, 21
	s_and_b64 s[26:27], s[0:1], exec
	s_cselect_b32 s13, s19, s25
	s_cselect_b32 s45, s18, s24
	s_add_u32 s22, s22, 0x40080
	v_readlane_b32 s46, v246, 22
	s_addc_u32 s23, s23, 0
	v_readlane_b32 s47, v246, 23
	s_add_u32 s46, s24, 0x100
	v_mov_b64_e32 v[0:1], 0
	s_addc_u32 s47, s25, 0
	s_mov_b32 s48, -2
	v_mov_b64_e32 v[2:3], 0
	v_mov_b64_e32 v[4:5], 0
	v_mov_b64_e32 v[6:7], 0
	v_mov_b64_e32 v[16:17], 0
	v_mov_b64_e32 v[18:19], 0
	v_mov_b64_e32 v[20:21], 0
	v_mov_b64_e32 v[22:23], 0
	v_mov_b64_e32 v[32:33], 0
	v_mov_b64_e32 v[34:35], 0
	v_mov_b64_e32 v[36:37], 0
	v_mov_b64_e32 v[38:39], 0
	v_mov_b64_e32 v[48:49], 0
	v_mov_b64_e32 v[50:51], 0
	v_mov_b64_e32 v[52:53], 0
	v_mov_b64_e32 v[54:55], 0
	v_mov_b64_e32 v[8:9], 0
	v_mov_b64_e32 v[10:11], 0
	v_mov_b64_e32 v[12:13], 0
	v_mov_b64_e32 v[14:15], 0
	v_mov_b64_e32 v[24:25], 0
	v_mov_b64_e32 v[26:27], 0
	v_mov_b64_e32 v[28:29], 0
	v_mov_b64_e32 v[30:31], 0
	v_mov_b64_e32 v[40:41], 0
	v_mov_b64_e32 v[42:43], 0
	v_mov_b64_e32 v[44:45], 0
	v_mov_b64_e32 v[46:47], 0
	v_mov_b64_e32 v[56:57], 0
	v_mov_b64_e32 v[58:59], 0
	v_mov_b64_e32 v[60:61], 0
	v_mov_b64_e32 v[62:63], 0
	v_mov_b64_e32 v[64:65], 0
	v_mov_b64_e32 v[66:67], 0
	v_mov_b64_e32 v[68:69], 0
	v_mov_b64_e32 v[70:71], 0
	v_mov_b64_e32 v[80:81], 0
	v_mov_b64_e32 v[82:83], 0
	v_mov_b64_e32 v[84:85], 0
	v_mov_b64_e32 v[86:87], 0
	v_mov_b64_e32 v[96:97], 0
	v_mov_b64_e32 v[98:99], 0
	v_mov_b64_e32 v[100:101], 0
	v_mov_b64_e32 v[102:103], 0
	v_mov_b64_e32 v[112:113], 0
	v_mov_b64_e32 v[114:115], 0
	v_mov_b64_e32 v[116:117], 0
	v_mov_b64_e32 v[118:119], 0
	v_mov_b64_e32 v[72:73], 0
	v_mov_b64_e32 v[74:75], 0
	v_mov_b64_e32 v[76:77], 0
	v_mov_b64_e32 v[78:79], 0
	v_mov_b64_e32 v[88:89], 0
	v_mov_b64_e32 v[90:91], 0
	v_mov_b64_e32 v[92:93], 0
	v_mov_b64_e32 v[94:95], 0
	v_mov_b64_e32 v[104:105], 0
	v_mov_b64_e32 v[106:107], 0
	v_mov_b64_e32 v[108:109], 0
	v_mov_b64_e32 v[110:111], 0
	v_mov_b64_e32 v[120:121], 0
	v_mov_b64_e32 v[122:123], 0
	v_mov_b64_e32 v[124:125], 0
	v_mov_b64_e32 v[126:127], 0
	v_readlane_b32 s52, v246, 28
	v_readlane_b32 s53, v246, 29
	v_readlane_b32 s54, v246, 30
	v_readlane_b32 s55, v246, 31

.LBB0_1017:
	s_add_u32 s30, s30, 0xb0080
	s_addc_u32 s31, s31, 0
	s_add_u32 s56, s34, 0x100
	v_mov_b64_e32 v[0:1], 0
	s_addc_u32 s57, s35, 0
	s_mov_b32 s60, -2
	v_mov_b64_e32 v[2:3], 0
	v_mov_b64_e32 v[4:5], 0
	v_mov_b64_e32 v[6:7], 0
	v_mov_b64_e32 v[12:13], 0
	v_mov_b64_e32 v[14:15], 0
	v_mov_b64_e32 v[20:21], 0
	v_mov_b64_e32 v[22:23], 0
	v_mov_b64_e32 v[24:25], 0
	v_mov_b64_e32 v[26:27], 0
	v_mov_b64_e32 v[36:37], 0
	v_mov_b64_e32 v[38:39], 0
	v_mov_b64_e32 v[40:41], 0
	v_mov_b64_e32 v[42:43], 0
	v_mov_b64_e32 v[52:53], 0
	v_mov_b64_e32 v[54:55], 0
	v_mov_b64_e32 v[8:9], 0
	v_mov_b64_e32 v[10:11], 0
	v_mov_b64_e32 v[16:17], 0
	v_mov_b64_e32 v[18:19], 0
	v_mov_b64_e32 v[28:29], 0
	v_mov_b64_e32 v[30:31], 0
	v_mov_b64_e32 v[32:33], 0
	v_mov_b64_e32 v[34:35], 0
	v_mov_b64_e32 v[44:45], 0
	v_mov_b64_e32 v[46:47], 0
	v_mov_b64_e32 v[48:49], 0
	v_mov_b64_e32 v[50:51], 0
	v_mov_b64_e32 v[56:57], 0
	v_mov_b64_e32 v[58:59], 0
	v_mov_b64_e32 v[60:61], 0
	v_mov_b64_e32 v[62:63], 0
	v_mov_b64_e32 v[64:65], 0
	v_mov_b64_e32 v[66:67], 0
	v_mov_b64_e32 v[68:69], 0
	v_mov_b64_e32 v[70:71], 0
	v_mov_b64_e32 v[72:73], 0
	v_mov_b64_e32 v[74:75], 0
	v_mov_b64_e32 v[84:85], 0
	v_mov_b64_e32 v[86:87], 0
	v_mov_b64_e32 v[88:89], 0
	v_mov_b64_e32 v[90:91], 0
	v_mov_b64_e32 v[100:101], 0
	v_mov_b64_e32 v[102:103], 0
	v_mov_b64_e32 v[104:105], 0
	v_mov_b64_e32 v[106:107], 0
	v_mov_b64_e32 v[116:117], 0
	v_mov_b64_e32 v[118:119], 0
	v_mov_b64_e32 v[76:77], 0
	v_mov_b64_e32 v[78:79], 0
	v_mov_b64_e32 v[80:81], 0
	v_mov_b64_e32 v[82:83], 0
	v_mov_b64_e32 v[92:93], 0
	v_mov_b64_e32 v[94:95], 0
	v_mov_b64_e32 v[96:97], 0
	v_mov_b64_e32 v[98:99], 0
	v_mov_b64_e32 v[108:109], 0
	v_mov_b64_e32 v[110:111], 0
	v_mov_b64_e32 v[112:113], 0
	v_mov_b64_e32 v[114:115], 0
	v_mov_b64_e32 v[120:121], 0
	v_mov_b64_e32 v[122:123], 0
	v_mov_b64_e32 v[124:125], 0
	v_mov_b64_e32 v[126:127], 0

.LBB0_1042:
	v_add_u32_e32 v147, s39, v146
	ds_read_b128 v[148:151], v147
	ds_read_b128 v[152:155], v147 offset:1024
	ds_read_b128 v[156:159], v147 offset:2048
	ds_read_b128 v[164:167], v147 offset:3072
	v_add_u32_e32 v147, s40, v146
	s_add_u32 s20, s12, s18
	ds_read_b128 v[174:177], v147
	ds_read_b128 v[178:181], v147 offset:1024
	ds_read_b128 v[182:185], v147 offset:2048
	ds_read_b128 v[186:189], v147 offset:3072
	s_addc_u32 s21, s13, s19
	s_add_u32 s20, s20, 0x100
	s_addc_u32 s21, s21, 0
	s_add_u32 s47, s44, s18
	s_addc_u32 s48, s45, s19
	s_cmpk_eq_i32 s18, 0x1500
	s_cselect_b32 s23, s17, s21
	s_cselect_b32 s22, s16, s20
	s_cselect_b32 s21, s5, s48
	s_cselect_b32 s20, s4, s47
	v_lshl_add_u64 v[160:161], v[140:141], 0, s[18:19]
	s_add_i32 m0, s29, 0xc000
	ds_read_b128 v[190:193], v144
	ds_read_b128 v[194:197], v144 offset:1024
	ds_read_b128 v[198:201], v144 offset:2048
	ds_read_b128 v[202:205], v144 offset:3072
	ds_read_b128 v[206:209], v144 offset:4096
	ds_read_b128 v[210:213], v144 offset:5120
	ds_read_b128 v[214:217], v144 offset:6144
	ds_read_b128 v[218:221], v144 offset:7168
	global_load_lds_dwordx4 v[160:161], off
	v_lshl_add_u64 v[160:161], v[142:143], 0, s[18:19]
	s_add_i32 m0, s29, 0xe000
	s_nop 0
	global_load_lds_dwordx4 v[160:161], off
	s_waitcnt vmcnt(8)
	s_waitcnt lgkmcnt(0)
	s_barrier
	s_waitcnt lgkmcnt(0)
	v_mfma_f32_16x16x32_bf16 v[124:127], v[148:151], v[190:193], v[124:127]
	v_mfma_f32_16x16x32_bf16 v[120:123], v[156:159], v[190:193], v[120:123]
	v_mfma_f32_16x16x32_bf16 v[116:119], v[148:151], v[198:201], v[116:119]
	v_mfma_f32_16x16x32_bf16 v[100:103], v[156:159], v[198:201], v[100:103]
	v_mfma_f32_16x16x32_bf16 v[104:107], v[148:151], v[206:209], v[104:107]
	v_mfma_f32_16x16x32_bf16 v[92:95], v[156:159], v[206:209], v[92:95]
	v_mfma_f32_16x16x32_bf16 v[96:99], v[148:151], v[214:217], v[96:99]
	v_mfma_f32_16x16x32_bf16 v[76:79], v[156:159], v[214:217], v[76:79]
	v_mfma_f32_16x16x32_bf16 v[124:127], v[152:155], v[194:197], v[124:127]
	v_mfma_f32_16x16x32_bf16 v[120:123], v[164:167], v[194:197], v[120:123]
	v_mfma_f32_16x16x32_bf16 v[116:119], v[152:155], v[202:205], v[116:119]
	v_mfma_f32_16x16x32_bf16 v[100:103], v[164:167], v[202:205], v[100:103]
	v_mfma_f32_16x16x32_bf16 v[104:107], v[152:155], v[210:213], v[104:107]
	v_mfma_f32_16x16x32_bf16 v[92:95], v[164:167], v[210:213], v[92:95]
	v_mfma_f32_16x16x32_bf16 v[96:99], v[152:155], v[218:221], v[96:99]
	v_mfma_f32_16x16x32_bf16 v[76:79], v[164:167], v[218:221], v[76:79]
	v_mfma_f32_16x16x32_bf16 v[112:115], v[174:177], v[190:193], v[112:115]
	v_mfma_f32_16x16x32_bf16 v[108:111], v[182:185], v[190:193], v[108:111]
	v_mfma_f32_16x16x32_bf16 v[88:91], v[174:177], v[198:201], v[88:91]
	v_mfma_f32_16x16x32_bf16 v[80:83], v[182:185], v[198:201], v[80:83]
	v_mfma_f32_16x16x32_bf16 v[84:87], v[174:177], v[206:209], v[84:87]
	v_mfma_f32_16x16x32_bf16 v[72:75], v[182:185], v[206:209], v[72:75]
	v_mfma_f32_16x16x32_bf16 v[68:71], v[174:177], v[214:217], v[68:71]
	v_mfma_f32_16x16x32_bf16 v[64:67], v[182:185], v[214:217], v[64:67]
	v_mfma_f32_16x16x32_bf16 v[112:115], v[178:181], v[194:197], v[112:115]
	v_mfma_f32_16x16x32_bf16 v[108:111], v[186:189], v[194:197], v[108:111]
	v_mfma_f32_16x16x32_bf16 v[88:91], v[178:181], v[202:205], v[88:91]
	v_mfma_f32_16x16x32_bf16 v[80:83], v[186:189], v[202:205], v[80:83]
	v_mfma_f32_16x16x32_bf16 v[84:87], v[178:181], v[210:213], v[84:87]
	v_mfma_f32_16x16x32_bf16 v[72:75], v[186:189], v[210:213], v[72:75]
	v_mfma_f32_16x16x32_bf16 v[68:71], v[178:181], v[218:221], v[68:71]
	v_mfma_f32_16x16x32_bf16 v[64:67], v[186:189], v[218:221], v[64:67]
	s_barrier
	s_add_i32 s47, s39, s28
	v_lshl_add_u64 v[160:161], s[20:21], 0, v[128:129]
	s_mov_b32 m0, s47
	ds_read_b128 v[190:193], v144 offset:16384
	ds_read_b128 v[194:197], v144 offset:17408
	ds_read_b128 v[198:201], v144 offset:18432
	ds_read_b128 v[202:205], v144 offset:19456
	ds_read_b128 v[206:209], v144 offset:20480
	ds_read_b128 v[210:213], v144 offset:21504
	ds_read_b128 v[214:217], v144 offset:22528
	ds_read_b128 v[218:221], v144 offset:23552
	global_load_lds_dwordx4 v[160:161], off
	s_add_i32 m0, s47, 0x2000
	s_add_u32 s48, s20, 0xb0000
	v_lshl_add_u64 v[168:169], s[20:21], 0, v[130:131]
	s_addc_u32 s49, s21, 0
	s_add_i32 s47, s40, s28
	global_load_lds_dwordx4 v[168:169], off
	v_lshl_add_u64 v[222:223], s[48:49], 0, v[128:129]
	s_mov_b32 m0, s47
	v_lshl_add_u64 v[224:225], s[22:23], 0, v[130:131]
	global_load_lds_dwordx4 v[222:223], off
	v_lshl_add_u64 v[222:223], s[48:49], 0, v[130:131]
	s_add_i32 m0, s47, 0x2000
	s_nop 0
	global_load_lds_dwordx4 v[222:223], off
	v_lshl_add_u64 v[222:223], s[22:23], 0, v[128:129]
	s_mov_b32 m0, s29
	s_nop 0
	global_load_lds_dwordx4 v[222:223], off
	s_mov_b32 m0, s30
	s_nop 0
	global_load_lds_dwordx4 v[224:225], off
	s_waitcnt vmcnt(8)
	s_waitcnt lgkmcnt(0)
	s_barrier
	s_waitcnt lgkmcnt(0)
	v_mfma_f32_16x16x32_bf16 v[60:63], v[148:151], v[190:193], v[60:63]
	v_mfma_f32_16x16x32_bf16 v[56:59], v[156:159], v[190:193], v[56:59]
	v_mfma_f32_16x16x32_bf16 v[44:47], v[148:151], v[198:201], v[44:47]
	v_mfma_f32_16x16x32_bf16 v[40:43], v[156:159], v[198:201], v[40:43]
	v_mfma_f32_16x16x32_bf16 v[28:31], v[148:151], v[206:209], v[28:31]
	v_mfma_f32_16x16x32_bf16 v[24:27], v[156:159], v[206:209], v[24:27]
	v_mfma_f32_16x16x32_bf16 v[12:15], v[148:151], v[214:217], v[12:15]
	v_mfma_f32_16x16x32_bf16 v[8:11], v[156:159], v[214:217], v[8:11]
	v_mfma_f32_16x16x32_bf16 v[60:63], v[152:155], v[194:197], v[60:63]
	v_mfma_f32_16x16x32_bf16 v[56:59], v[164:167], v[194:197], v[56:59]
	v_mfma_f32_16x16x32_bf16 v[44:47], v[152:155], v[202:205], v[44:47]
	v_mfma_f32_16x16x32_bf16 v[40:43], v[164:167], v[202:205], v[40:43]
	v_mfma_f32_16x16x32_bf16 v[28:31], v[152:155], v[210:213], v[28:31]
	v_mfma_f32_16x16x32_bf16 v[24:27], v[164:167], v[210:213], v[24:27]
	v_mfma_f32_16x16x32_bf16 v[12:15], v[152:155], v[218:221], v[12:15]
	v_mfma_f32_16x16x32_bf16 v[8:11], v[164:167], v[218:221], v[8:11]
	v_mfma_f32_16x16x32_bf16 v[52:55], v[174:177], v[190:193], v[52:55]
	v_mfma_f32_16x16x32_bf16 v[48:51], v[182:185], v[190:193], v[48:51]
	v_mfma_f32_16x16x32_bf16 v[36:39], v[174:177], v[198:201], v[36:39]
	v_mfma_f32_16x16x32_bf16 v[32:35], v[182:185], v[198:201], v[32:35]
	v_mfma_f32_16x16x32_bf16 v[20:23], v[174:177], v[206:209], v[20:23]
	v_mfma_f32_16x16x32_bf16 v[16:19], v[182:185], v[206:209], v[16:19]
	v_mfma_f32_16x16x32_bf16 v[4:7], v[174:177], v[214:217], v[4:7]
	v_mfma_f32_16x16x32_bf16 v[0:3], v[182:185], v[214:217], v[0:3]
	v_mfma_f32_16x16x32_bf16 v[52:55], v[178:181], v[194:197], v[52:55]
	v_mfma_f32_16x16x32_bf16 v[48:51], v[186:189], v[194:197], v[48:51]
	v_mfma_f32_16x16x32_bf16 v[36:39], v[178:181], v[202:205], v[36:39]
	v_mfma_f32_16x16x32_bf16 v[32:35], v[186:189], v[202:205], v[32:35]
	v_mfma_f32_16x16x32_bf16 v[20:23], v[178:181], v[210:213], v[20:23]
	v_mfma_f32_16x16x32_bf16 v[16:19], v[186:189], v[210:213], v[16:19]
	v_mfma_f32_16x16x32_bf16 v[4:7], v[178:181], v[218:221], v[4:7]
	v_mfma_f32_16x16x32_bf16 v[0:3], v[186:189], v[218:221], v[0:3]
	s_barrier
	s_add_i32 s47, 0, 0x18000
	v_add_u32_e32 v147, s47, v146
	s_add_i32 s48, 0, 0x1c000
	ds_read_b128 v[148:151], v147
	ds_read_b128 v[152:155], v147 offset:1024
	ds_read_b128 v[156:159], v147 offset:2048
	ds_read_b128 v[164:167], v147 offset:3072
	v_add_u32_e32 v147, s48, v146
	ds_read_b128 v[174:177], v147
	ds_read_b128 v[178:181], v147 offset:1024
	ds_read_b128 v[182:185], v147 offset:2048
	ds_read_b128 v[186:189], v147 offset:3072
	s_add_u32 s22, s22, 0xb0000
	s_addc_u32 s23, s23, 0
	s_mov_b32 m0, s31
	v_lshl_add_u64 v[226:227], s[22:23], 0, v[128:129]
	ds_read_b128 v[190:193], v144 offset:32768
	ds_read_b128 v[194:197], v144 offset:33792
	ds_read_b128 v[198:201], v144 offset:34816
	ds_read_b128 v[202:205], v144 offset:35840
	ds_read_b128 v[206:209], v144 offset:36864
	ds_read_b128 v[210:213], v144 offset:37888
	ds_read_b128 v[214:217], v144 offset:38912
	ds_read_b128 v[218:221], v144 offset:39936
	global_load_lds_dwordx4 v[226:227], off
	v_lshl_add_u64 v[226:227], s[22:23], 0, v[130:131]
	s_mov_b32 m0, s34
	s_nop 0
	global_load_lds_dwordx4 v[226:227], off
	s_waitcnt vmcnt(8)
	s_waitcnt lgkmcnt(0)
	s_barrier
	s_waitcnt lgkmcnt(0)
	v_mfma_f32_16x16x32_bf16 v[124:127], v[148:151], v[190:193], v[124:127]
	v_mfma_f32_16x16x32_bf16 v[120:123], v[156:159], v[190:193], v[120:123]
	v_mfma_f32_16x16x32_bf16 v[116:119], v[148:151], v[198:201], v[116:119]
	v_mfma_f32_16x16x32_bf16 v[100:103], v[156:159], v[198:201], v[100:103]
	v_mfma_f32_16x16x32_bf16 v[104:107], v[148:151], v[206:209], v[104:107]
	v_mfma_f32_16x16x32_bf16 v[92:95], v[156:159], v[206:209], v[92:95]
	v_mfma_f32_16x16x32_bf16 v[96:99], v[148:151], v[214:217], v[96:99]
	v_mfma_f32_16x16x32_bf16 v[76:79], v[156:159], v[214:217], v[76:79]
	v_mfma_f32_16x16x32_bf16 v[124:127], v[152:155], v[194:197], v[124:127]
	v_mfma_f32_16x16x32_bf16 v[120:123], v[164:167], v[194:197], v[120:123]
	v_mfma_f32_16x16x32_bf16 v[116:119], v[152:155], v[202:205], v[116:119]
	v_mfma_f32_16x16x32_bf16 v[100:103], v[164:167], v[202:205], v[100:103]
	v_mfma_f32_16x16x32_bf16 v[104:107], v[152:155], v[210:213], v[104:107]
	v_mfma_f32_16x16x32_bf16 v[92:95], v[164:167], v[210:213], v[92:95]
	v_mfma_f32_16x16x32_bf16 v[96:99], v[152:155], v[218:221], v[96:99]
	v_mfma_f32_16x16x32_bf16 v[76:79], v[164:167], v[218:221], v[76:79]
	v_mfma_f32_16x16x32_bf16 v[112:115], v[174:177], v[190:193], v[112:115]
	v_mfma_f32_16x16x32_bf16 v[108:111], v[182:185], v[190:193], v[108:111]
	v_mfma_f32_16x16x32_bf16 v[88:91], v[174:177], v[198:201], v[88:91]
	v_mfma_f32_16x16x32_bf16 v[80:83], v[182:185], v[198:201], v[80:83]
	v_mfma_f32_16x16x32_bf16 v[84:87], v[174:177], v[206:209], v[84:87]
	v_mfma_f32_16x16x32_bf16 v[72:75], v[182:185], v[206:209], v[72:75]
	v_mfma_f32_16x16x32_bf16 v[68:71], v[174:177], v[214:217], v[68:71]
	v_mfma_f32_16x16x32_bf16 v[64:67], v[182:185], v[214:217], v[64:67]
	v_mfma_f32_16x16x32_bf16 v[112:115], v[178:181], v[194:197], v[112:115]
	v_mfma_f32_16x16x32_bf16 v[108:111], v[186:189], v[194:197], v[108:111]
	v_mfma_f32_16x16x32_bf16 v[88:91], v[178:181], v[202:205], v[88:91]
	v_mfma_f32_16x16x32_bf16 v[80:83], v[186:189], v[202:205], v[80:83]
	v_mfma_f32_16x16x32_bf16 v[84:87], v[178:181], v[210:213], v[84:87]
	v_mfma_f32_16x16x32_bf16 v[72:75], v[186:189], v[210:213], v[72:75]
	v_mfma_f32_16x16x32_bf16 v[68:71], v[178:181], v[218:221], v[68:71]
	v_mfma_f32_16x16x32_bf16 v[64:67], v[186:189], v[218:221], v[64:67]
	s_barrier
	s_add_i32 s22, s47, s28
	v_lshl_add_u64 v[160:161], v[160:161], 0, s[14:15]
	s_mov_b32 m0, s22
	ds_read_b128 v[190:193], v144 offset:49152
	ds_read_b128 v[194:197], v144 offset:50176
	ds_read_b128 v[198:201], v144 offset:51200
	ds_read_b128 v[202:205], v144 offset:52224
	ds_read_b128 v[206:209], v144 offset:53248
	ds_read_b128 v[210:213], v144 offset:54272
	ds_read_b128 v[214:217], v144 offset:55296
	ds_read_b128 v[218:221], v144 offset:56320
	global_load_lds_dwordx4 v[160:161], off
	s_add_i32 m0, s22, 0x2000
	s_add_u32 s20, s20, 0xb0080
	v_lshl_add_u64 v[160:161], v[168:169], 0, s[14:15]
	s_addc_u32 s21, s21, 0
	s_add_i32 s22, s48, s28
	global_load_lds_dwordx4 v[160:161], off
	v_lshl_add_u64 v[160:161], s[20:21], 0, v[128:129]
	s_mov_b32 m0, s22
	s_nop 0
	global_load_lds_dwordx4 v[160:161], off
	v_lshl_add_u64 v[160:161], s[20:21], 0, v[130:131]
	s_add_i32 m0, s22, 0x2000
	s_nop 0
	global_load_lds_dwordx4 v[160:161], off
	v_lshl_add_u64 v[160:161], v[222:223], 0, s[14:15]
	s_mov_b32 m0, s37
	s_nop 0
	global_load_lds_dwordx4 v[160:161], off
	v_lshl_add_u64 v[160:161], v[224:225], 0, s[14:15]
	s_mov_b32 m0, s38
	s_nop 0
	global_load_lds_dwordx4 v[160:161], off
	s_waitcnt vmcnt(8)
	s_waitcnt lgkmcnt(0)
	s_barrier
	s_waitcnt lgkmcnt(0)
	v_mfma_f32_16x16x32_bf16 v[60:63], v[148:151], v[190:193], v[60:63]
	v_mfma_f32_16x16x32_bf16 v[56:59], v[156:159], v[190:193], v[56:59]
	v_mfma_f32_16x16x32_bf16 v[44:47], v[148:151], v[198:201], v[44:47]
	v_mfma_f32_16x16x32_bf16 v[40:43], v[156:159], v[198:201], v[40:43]
	v_mfma_f32_16x16x32_bf16 v[28:31], v[148:151], v[206:209], v[28:31]
	v_mfma_f32_16x16x32_bf16 v[24:27], v[156:159], v[206:209], v[24:27]
	v_mfma_f32_16x16x32_bf16 v[12:15], v[148:151], v[214:217], v[12:15]
	v_mfma_f32_16x16x32_bf16 v[8:11], v[156:159], v[214:217], v[8:11]
	v_mfma_f32_16x16x32_bf16 v[60:63], v[152:155], v[194:197], v[60:63]
	v_mfma_f32_16x16x32_bf16 v[56:59], v[164:167], v[194:197], v[56:59]
	v_mfma_f32_16x16x32_bf16 v[44:47], v[152:155], v[202:205], v[44:47]
	v_mfma_f32_16x16x32_bf16 v[40:43], v[164:167], v[202:205], v[40:43]
	v_mfma_f32_16x16x32_bf16 v[28:31], v[152:155], v[210:213], v[28:31]
	v_mfma_f32_16x16x32_bf16 v[24:27], v[164:167], v[210:213], v[24:27]
	v_mfma_f32_16x16x32_bf16 v[12:15], v[152:155], v[218:221], v[12:15]
	v_mfma_f32_16x16x32_bf16 v[8:11], v[164:167], v[218:221], v[8:11]
	v_mfma_f32_16x16x32_bf16 v[52:55], v[174:177], v[190:193], v[52:55]
	v_mfma_f32_16x16x32_bf16 v[48:51], v[182:185], v[190:193], v[48:51]
	v_mfma_f32_16x16x32_bf16 v[36:39], v[174:177], v[198:201], v[36:39]
	v_mfma_f32_16x16x32_bf16 v[32:35], v[182:185], v[198:201], v[32:35]
	v_mfma_f32_16x16x32_bf16 v[20:23], v[174:177], v[206:209], v[20:23]
	v_mfma_f32_16x16x32_bf16 v[16:19], v[182:185], v[206:209], v[16:19]
	v_mfma_f32_16x16x32_bf16 v[4:7], v[174:177], v[214:217], v[4:7]
	v_mfma_f32_16x16x32_bf16 v[0:3], v[182:185], v[214:217], v[0:3]
	v_mfma_f32_16x16x32_bf16 v[52:55], v[178:181], v[194:197], v[52:55]
	v_mfma_f32_16x16x32_bf16 v[48:51], v[186:189], v[194:197], v[48:51]
	v_mfma_f32_16x16x32_bf16 v[36:39], v[178:181], v[202:205], v[36:39]
	v_mfma_f32_16x16x32_bf16 v[32:35], v[186:189], v[202:205], v[32:35]
	v_mfma_f32_16x16x32_bf16 v[20:23], v[178:181], v[210:213], v[20:23]
	v_mfma_f32_16x16x32_bf16 v[16:19], v[186:189], v[210:213], v[16:19]
	v_mfma_f32_16x16x32_bf16 v[4:7], v[178:181], v[218:221], v[4:7]
	v_mfma_f32_16x16x32_bf16 v[0:3], v[186:189], v[218:221], v[0:3]
	s_barrier
	s_add_i32 s46, s46, 2
	s_add_u32 s18, s18, 0x100
	s_addc_u32 s19, s19, 0
	s_cmp_gt_u32 s46, 41
	s_cbranch_scc0 .LBB0_1042
	s_add_u32 s18, s44, 0xffffff00
	s_addc_u32 s19, s45, -1
	s_and_b64 vcc, exec, s[2:3]
	s_cbranch_vccnz .LBB0_1045
	v_mov_b64_e32 v[0:1], 0
	s_mov_b32 s10, s41
	s_mov_b32 s24, s42
	s_mov_b64 s[12:13], s[16:17]
	s_mov_b32 s36, s43
	v_mov_b64_e32 v[2:3], 0
	v_mov_b64_e32 v[4:5], 0
	v_mov_b64_e32 v[6:7], 0
	v_mov_b64_e32 v[16:17], 0
	v_mov_b64_e32 v[18:19], 0
	v_mov_b64_e32 v[20:21], 0
	v_mov_b64_e32 v[22:23], 0
	v_mov_b64_e32 v[32:33], 0
	v_mov_b64_e32 v[34:35], 0
	v_mov_b64_e32 v[36:37], 0
	v_mov_b64_e32 v[38:39], 0
	v_mov_b64_e32 v[48:49], 0
	v_mov_b64_e32 v[50:51], 0
	v_mov_b64_e32 v[52:53], 0
	v_mov_b64_e32 v[54:55], 0
	v_mov_b64_e32 v[8:9], 0
	v_mov_b64_e32 v[10:11], 0
	v_mov_b64_e32 v[12:13], 0
	v_mov_b64_e32 v[14:15], 0
	v_mov_b64_e32 v[24:25], 0
	v_mov_b64_e32 v[26:27], 0
	v_mov_b64_e32 v[28:29], 0
	v_mov_b64_e32 v[30:31], 0
	v_mov_b64_e32 v[40:41], 0
	v_mov_b64_e32 v[42:43], 0
	v_mov_b64_e32 v[44:45], 0
	v_mov_b64_e32 v[46:47], 0
	v_mov_b64_e32 v[56:57], 0
	v_mov_b64_e32 v[58:59], 0
	v_mov_b64_e32 v[60:61], 0
	v_mov_b64_e32 v[62:63], 0
	v_mov_b64_e32 v[64:65], 0
	v_mov_b64_e32 v[66:67], 0
	v_mov_b64_e32 v[68:69], 0
	v_mov_b64_e32 v[70:71], 0
	v_mov_b64_e32 v[72:73], 0
	v_mov_b64_e32 v[74:75], 0
	v_mov_b64_e32 v[84:85], 0
	v_mov_b64_e32 v[86:87], 0
	v_mov_b64_e32 v[80:81], 0
	v_mov_b64_e32 v[82:83], 0
	v_mov_b64_e32 v[88:89], 0
	v_mov_b64_e32 v[90:91], 0
	v_mov_b64_e32 v[108:109], 0
	v_mov_b64_e32 v[110:111], 0
	v_mov_b64_e32 v[112:113], 0
	v_mov_b64_e32 v[114:115], 0
	v_mov_b64_e32 v[76:77], 0
	v_mov_b64_e32 v[78:79], 0
	v_mov_b64_e32 v[96:97], 0
	v_mov_b64_e32 v[98:99], 0
	v_mov_b64_e32 v[92:93], 0
	v_mov_b64_e32 v[94:95], 0
	v_mov_b64_e32 v[104:105], 0
	v_mov_b64_e32 v[106:107], 0
	v_mov_b64_e32 v[100:101], 0
	v_mov_b64_e32 v[102:103], 0
	v_mov_b64_e32 v[116:117], 0
	v_mov_b64_e32 v[118:119], 0
	v_mov_b64_e32 v[120:121], 0
	v_mov_b64_e32 v[122:123], 0
	v_mov_b64_e32 v[124:125], 0
	v_mov_b64_e32 v[126:127], 0
	s_andn2_b64 vcc, exec, s[0:1]
	s_cbranch_vccnz .LBB0_1046
	s_branch .LBB0_1047
